# LN1 and LN2 loops software-pipelined: gamma/beta hoisted into registers, both rows' stats reduced up front, next trip's loads issued as each chunk is consumed, counted waits; nt on streaming row loads
# speedup vs baseline: 1.0387x; 1.0132x over previous
.LBB0_1739:
	s_or_b64 exec, exec, s[4:5]
	v_mov_b32_e32 v0, v228
	s_barrier
	v_readlane_b32 s5, v251, 2
	v_readfirstlane_b32 s4, v0
	s_ashr_i32 s4, s4, 6
	s_add_i32 s20, s4, s5
	s_add_u32 s16, s90, 0x199c0800
	s_addc_u32 s17, s91, 0
	s_add_u32 s12, s90, 0x38bb0800
	s_addc_u32 s13, s91, 0
	s_cmp_gt_i32 s20, 0x100ff
	s_cbranch_scc1 .LBB0_1752
	v_and_b32_e32 v4, 63, v0
	v_mov_b32_e32 v32, 0
	v_lshlrev_b32_e32 v0, 4, v4
	v_mov_b32_e32 v1, v32
	v_lshlrev_b32_e32 v2, 3, v4
	v_mov_b32_e32 v3, v32
	v_cmp_gt_u32_e64 s[4:5], 16, v4
	v_lshl_add_u64 v[34:35], s[0:1], 0, v[0:1]
	v_lshl_add_u64 v[36:37], s[14:15], 0, v[2:3]
	v_cmp_eq_u32_e64 s[6:7], 0, v4
	v_lshl_add_u64 v[38:39], s[42:43], 0, v[0:1]
	v_lshl_add_u64 v[40:41], s[44:45], 0, v[0:1]
	v_lshl_add_u64 v[42:43], s[16:17], 0, v[2:3]
	s_mov_b32 s24, 0x3a800000
	s_mov_b32 s25, 0xf800000
	v_mov_b32_e32 v48, 0x260
	global_load_dwordx4 v[60:63], v[38:39], off
	global_load_dwordx4 v[76:79], v[40:41], off
	global_load_dwordx4 v[64:67], v[38:39], off offset:1024
	global_load_dwordx4 v[80:83], v[40:41], off offset:1024
	global_load_dwordx4 v[68:71], v[38:39], off offset:2048
	global_load_dwordx4 v[84:87], v[40:41], off offset:2048
	global_load_dwordx4 v[72:75], v[38:39], off offset:3072
	global_load_dwordx4 v[88:91], v[40:41], off offset:3072
	v_mov_b32_e32 v132, 0
	v_mov_b32_e32 v133, 0
	v_mov_b32_e32 v134, 0
	v_mov_b32_e32 v135, 0
	s_add_i32 s14, s20, s76
	s_cmp_lt_i32 s14, 0x10100
	s_cselect_b32 s14, s14, s20
	s_ashr_i32 s21, s20, 31
	s_ashr_i32 s15, s14, 31
	s_lshl_b64 s[8:9], s[20:21], 12
	v_lshl_add_u64 v[136:137], v[34:35], 0, s[8:9]
	s_lshl_b64 s[8:9], s[14:15], 12
	v_lshl_add_u64 v[138:139], v[34:35], 0, s[8:9]
	s_lshl_b64 s[8:9], s[20:21], 7
	v_lshl_add_u64 v[144:145], v[36:37], 0, s[8:9]
	s_lshl_b64 s[8:9], s[14:15], 7
	v_lshl_add_u64 v[146:147], v[36:37], 0, s[8:9]
	s_and_saveexec_b64 s[8:9], s[4:5]
	global_load_dwordx2 v[132:133], v[144:145], off
	global_load_dwordx2 v[134:135], v[146:147], off
	s_mov_b64 exec, s[8:9]
	global_load_dwordx4 v[100:103], v[136:137], off nt
	global_load_dwordx4 v[104:107], v[136:137], off offset:1024 nt
	global_load_dwordx4 v[108:111], v[136:137], off offset:2048 nt
	global_load_dwordx4 v[112:115], v[136:137], off offset:3072 nt
	global_load_dwordx4 v[116:119], v[138:139], off nt
	global_load_dwordx4 v[120:123], v[138:139], off offset:1024 nt
	global_load_dwordx4 v[124:127], v[138:139], off offset:2048 nt
	global_load_dwordx4 v[128:131], v[138:139], off offset:3072 nt
	s_waitcnt vmcnt(0)
.Lln1_loop:
	s_waitcnt vmcnt(16)
	v_mov_b32_e32 v46, v132
	v_mov_b32_e32 v44, v133
	v_mov_b32_e32 v45, v134
	v_mov_b32_e32 v33, v135
	v_mov_b32_e32 v47, v46
	s_nop 1
	v_mov_b32_dpp v47, v47 quad_perm:[1,0,3,2] row_mask:0xf bank_mask:0xf
	v_add_f32_e32 v46, v46, v47
	v_mov_b32_e32 v47, v46
	s_nop 1
	v_mov_b32_dpp v47, v47 quad_perm:[2,3,0,1] row_mask:0xf bank_mask:0xf
	v_add_f32_e32 v46, v46, v47
	v_mov_b32_e32 v47, v46
	s_nop 1
	v_mov_b32_dpp v47, v47 row_ror:4 row_mask:0xf bank_mask:0xf
	v_add_f32_e32 v46, v46, v47
	v_mov_b32_e32 v47, v46
	s_nop 1
	v_mov_b32_dpp v47, v47 row_ror:8 row_mask:0xf bank_mask:0xf
	v_add_f32_e32 v46, v46, v47
	v_mov_b32_e32 v47, v44
	v_readfirstlane_b32 s8, v46
	s_nop 0
	v_mov_b32_dpp v47, v47 quad_perm:[1,0,3,2] row_mask:0xf bank_mask:0xf
	v_add_f32_e32 v44, v44, v47
	v_mov_b32_e32 v47, v44
	v_cvt_i32_f32_e32 v46, s8
	v_cvt_f32_i32_e32 v46, v46
	v_mov_b32_dpp v47, v47 quad_perm:[2,3,0,1] row_mask:0xf bank_mask:0xf
	v_add_f32_e32 v44, v44, v47
	v_mov_b32_e32 v47, v44
	v_mul_f32_e32 v46, 0x3a800000, v46
	s_nop 0
	v_mov_b32_dpp v47, v47 row_ror:4 row_mask:0xf bank_mask:0xf
	v_add_f32_e32 v44, v44, v47
	v_mov_b32_e32 v47, v44
	s_nop 1
	v_mov_b32_dpp v47, v47 row_ror:8 row_mask:0xf bank_mask:0xf
	v_add_f32_e32 v44, v44, v47
	v_mul_f32_e32 v47, v46, v46
	v_readfirstlane_b32 s8, v44
	s_nop 1
	v_cvt_i32_f32_e32 v44, s8
	v_cvt_f32_i32_e32 v44, v44
	v_fma_f32 v44, v44, s24, -v47
	v_max_f32_e32 v44, 0, v44
	v_add_f32_e32 v44, 0x3727c5ac, v44
	v_mul_f32_e32 v47, 0x4f800000, v44
	v_cmp_gt_f32_e32 vcc, s25, v44
	s_nop 1
	v_cndmask_b32_e32 v44, v44, v47, vcc
	v_sqrt_f32_e32 v47, v44
	s_nop 0
	v_add_u32_e32 v49, -1, v47
	v_fma_f32 v50, -v49, v47, v44
	v_cmp_ge_f32_e64 s[8:9], 0, v50
	v_add_u32_e32 v50, 1, v47
	s_nop 0
	v_cndmask_b32_e64 v49, v47, v49, s[8:9]
	v_fma_f32 v47, -v50, v47, v44
	v_cmp_lt_f32_e64 s[8:9], 0, v47
	s_nop 1
	v_cndmask_b32_e64 v47, v49, v50, s[8:9]
	v_mul_f32_e32 v49, 0x37800000, v47
	v_cndmask_b32_e32 v47, v47, v49, vcc
	v_cmp_class_f32_e32 vcc, v44, v48
	s_nop 1
	v_cndmask_b32_e32 v44, v47, v44, vcc
	v_div_scale_f32 v47, s[8:9], v44, v44, 1.0
	v_rcp_f32_e32 v49, v47
	s_nop 0
	v_fma_f32 v50, -v47, v49, 1.0
	v_fmac_f32_e32 v49, v50, v49
	v_div_scale_f32 v50, vcc, 1.0, v44, 1.0
	v_mul_f32_e32 v51, v50, v49
	v_fma_f32 v52, -v47, v51, v50
	v_fmac_f32_e32 v51, v52, v49
	v_fma_f32 v47, -v47, v51, v50
	v_div_fmas_f32 v47, v47, v49, v51
	v_div_fixup_f32 v44, v47, v44, 1.0
	v_mov_b32_e32 v16, v45
	s_ashr_i32 s15, s14, 31
	s_nop 0
	v_mov_b32_dpp v16, v16 quad_perm:[1,0,3,2] row_mask:0xf bank_mask:0xf
	v_add_f32_e32 v16, v45, v16
	v_mov_b32_e32 v17, v16
	s_nop 1
	v_mov_b32_dpp v17, v17 quad_perm:[2,3,0,1] row_mask:0xf bank_mask:0xf
	v_add_f32_e32 v16, v16, v17
	v_mov_b32_e32 v17, v16
	s_nop 1
	v_mov_b32_dpp v17, v17 row_ror:4 row_mask:0xf bank_mask:0xf
	v_add_f32_e32 v16, v16, v17
	v_mov_b32_e32 v17, v16
	s_nop 1
	v_mov_b32_dpp v17, v17 row_ror:8 row_mask:0xf bank_mask:0xf
	v_add_f32_e32 v16, v16, v17
	v_mov_b32_e32 v17, v33
	v_readfirstlane_b32 s8, v16
	s_nop 0
	v_mov_b32_dpp v17, v17 quad_perm:[1,0,3,2] row_mask:0xf bank_mask:0xf
	v_add_f32_e32 v17, v33, v17
	v_mov_b32_e32 v18, v17
	v_cvt_i32_f32_e32 v16, s8
	v_cvt_f32_i32_e32 v16, v16
	v_mov_b32_dpp v18, v18 quad_perm:[2,3,0,1] row_mask:0xf bank_mask:0xf
	v_add_f32_e32 v17, v17, v18
	v_mov_b32_e32 v18, v17
	v_mul_f32_e32 v16, 0x3a800000, v16
	s_nop 0
	v_mov_b32_dpp v18, v18 row_ror:4 row_mask:0xf bank_mask:0xf
	v_add_f32_e32 v17, v17, v18
	v_mov_b32_e32 v18, v17
	s_nop 1
	v_mov_b32_dpp v18, v18 row_ror:8 row_mask:0xf bank_mask:0xf
	v_add_f32_e32 v17, v17, v18
	v_mul_f32_e32 v18, v16, v16
	v_readfirstlane_b32 s8, v17
	s_nop 1
	v_cvt_i32_f32_e32 v17, s8
	v_cvt_f32_i32_e32 v17, v17
	v_fma_f32 v17, v17, s24, -v18
	v_max_f32_e32 v17, 0, v17
	v_add_f32_e32 v17, 0x3727c5ac, v17
	v_mul_f32_e32 v18, 0x4f800000, v17
	v_cmp_gt_f32_e32 vcc, s25, v17
	s_nop 1
	v_cndmask_b32_e32 v17, v17, v18, vcc
	v_sqrt_f32_e32 v18, v17
	s_nop 0
	v_add_u32_e32 v19, -1, v18
	v_fma_f32 v20, -v19, v18, v17
	v_cmp_ge_f32_e64 s[8:9], 0, v20
	v_add_u32_e32 v20, 1, v18
	s_nop 0
	v_cndmask_b32_e64 v19, v18, v19, s[8:9]
	v_fma_f32 v18, -v20, v18, v17
	v_cmp_lt_f32_e64 s[8:9], 0, v18
	s_nop 1
	v_cndmask_b32_e64 v18, v19, v20, s[8:9]
	v_mul_f32_e32 v19, 0x37800000, v18
	v_cndmask_b32_e32 v18, v18, v19, vcc
	v_cmp_class_f32_e32 vcc, v17, v48
	s_nop 1
	v_cndmask_b32_e32 v17, v18, v17, vcc
	v_div_scale_f32 v18, s[8:9], v17, v17, 1.0
	v_rcp_f32_e32 v19, v18
	s_nop 0
	v_fma_f32 v20, -v18, v19, 1.0
	v_fmac_f32_e32 v19, v20, v19
	v_div_scale_f32 v20, vcc, 1.0, v17, 1.0
	v_mul_f32_e32 v21, v20, v19
	v_fma_f32 v22, -v18, v21, v20
	v_fmac_f32_e32 v21, v22, v19
	v_fma_f32 v18, -v18, v21, v20
	v_div_fmas_f32 v18, v18, v19, v21
	v_div_fixup_f32 v18, v18, v17, 1.0
	s_and_saveexec_b64 s[8:9], s[6:7]
	s_lshl_b64 s[22:23], s[20:21], 3
	s_add_u32 s22, s12, s22
	s_addc_u32 s23, s13, s23
	v_mov_b32_e32 v47, v44
	global_store_dwordx2 v32, v[46:47], s[22:23]
	s_lshl_b64 s[18:19], s[14:15], 3
	s_add_u32 s18, s12, s18
	s_addc_u32 s19, s13, s19
	v_mov_b32_e32 v17, v18
	global_store_dwordx2 v32, v[16:17], s[18:19]
	s_mov_b64 exec, s[8:9]
	s_lshl_b64 s[8:9], s[20:21], 11
	v_lshl_add_u64 v[140:141], v[42:43], 0, s[8:9]
	s_lshl_b64 s[8:9], s[14:15], 11
	v_lshl_add_u64 v[142:143], v[42:43], 0, s[8:9]
	s_lshl_b32 s8, s76, 1
	s_add_i32 s20, s20, s8
	s_add_i32 s14, s20, s76
	s_cmp_lt_i32 s14, 0x10100
	s_cselect_b32 s14, s14, s20
	s_cmp_lt_i32 s20, 0x10100
	s_cselect_b64 s[26:27], -1, 0
	s_cbranch_scc0 .Lln1_dummy
	s_ashr_i32 s21, s20, 31
	s_ashr_i32 s15, s14, 31
	s_lshl_b64 s[8:9], s[20:21], 12
	v_lshl_add_u64 v[136:137], v[34:35], 0, s[8:9]
	s_lshl_b64 s[8:9], s[14:15], 12
	v_lshl_add_u64 v[138:139], v[34:35], 0, s[8:9]
	s_lshl_b64 s[8:9], s[20:21], 7
	v_lshl_add_u64 v[144:145], v[36:37], 0, s[8:9]
	s_lshl_b64 s[8:9], s[14:15], 7
	v_lshl_add_u64 v[146:147], v[36:37], 0, s[8:9]
	s_branch .Lln1_addr
.Lln1_dummy:
	v_mov_b64_e32 v[136:137], v[38:39]
	v_mov_b64_e32 v[138:139], v[38:39]
	v_mov_b64_e32 v[144:145], v[36:37]
	v_mov_b64_e32 v[146:147], v[36:37]
.Lln1_addr:
	s_and_saveexec_b64 s[8:9], s[4:5]
	global_load_dwordx2 v[132:133], v[144:145], off
	global_load_dwordx2 v[134:135], v[146:147], off
	s_mov_b64 exec, s[8:9]
	s_waitcnt vmcnt(18)
	v_sub_f32_e32 v101, v101, v46
	v_sub_f32_e32 v100, v100, v46
	v_sub_f32_e32 v103, v103, v46
	v_sub_f32_e32 v102, v102, v46
	v_pk_mul_f32 v[100:101], v[100:101], v[44:45] op_sel_hi:[1,0]
	v_pk_mul_f32 v[102:103], v[102:103], v[44:45] op_sel_hi:[1,0]
	v_pk_fma_f32 v[100:101], v[100:101], v[60:61], v[76:77]
	v_pk_fma_f32 v[102:103], v[102:103], v[62:63], v[78:79]
	v_cvt_pk_bf16_f32 v100, v100, v101
	v_cvt_pk_bf16_f32 v101, v102, v103
	global_store_dwordx2 v[140:141], v[100:101], off nt
	global_load_dwordx4 v[100:103], v[136:137], off nt
	s_waitcnt vmcnt(18)
	v_sub_f32_e32 v105, v105, v46
	v_sub_f32_e32 v104, v104, v46
	v_sub_f32_e32 v107, v107, v46
	v_sub_f32_e32 v106, v106, v46
	v_pk_mul_f32 v[104:105], v[104:105], v[44:45] op_sel_hi:[1,0]
	v_pk_mul_f32 v[106:107], v[106:107], v[44:45] op_sel_hi:[1,0]
	v_pk_fma_f32 v[104:105], v[104:105], v[64:65], v[80:81]
	v_pk_fma_f32 v[106:107], v[106:107], v[66:67], v[82:83]
	v_cvt_pk_bf16_f32 v104, v104, v105
	v_cvt_pk_bf16_f32 v105, v106, v107
	global_store_dwordx2 v[140:141], v[104:105], off offset:512 nt
	global_load_dwordx4 v[104:107], v[136:137], off offset:1024 nt
	s_waitcnt vmcnt(18)
	v_sub_f32_e32 v109, v109, v46
	v_sub_f32_e32 v108, v108, v46
	v_sub_f32_e32 v111, v111, v46
	v_sub_f32_e32 v110, v110, v46
	v_pk_mul_f32 v[108:109], v[108:109], v[44:45] op_sel_hi:[1,0]
	v_pk_mul_f32 v[110:111], v[110:111], v[44:45] op_sel_hi:[1,0]
	v_pk_fma_f32 v[108:109], v[108:109], v[68:69], v[84:85]
	v_pk_fma_f32 v[110:111], v[110:111], v[70:71], v[86:87]
	v_cvt_pk_bf16_f32 v108, v108, v109
	v_cvt_pk_bf16_f32 v109, v110, v111
	global_store_dwordx2 v[140:141], v[108:109], off offset:1024 nt
	global_load_dwordx4 v[108:111], v[136:137], off offset:2048 nt
	s_waitcnt vmcnt(18)
	v_sub_f32_e32 v113, v113, v46
	v_sub_f32_e32 v112, v112, v46
	v_sub_f32_e32 v115, v115, v46
	v_sub_f32_e32 v114, v114, v46
	v_pk_mul_f32 v[112:113], v[112:113], v[44:45] op_sel_hi:[1,0]
	v_pk_mul_f32 v[114:115], v[114:115], v[44:45] op_sel_hi:[1,0]
	v_pk_fma_f32 v[112:113], v[112:113], v[72:73], v[88:89]
	v_pk_fma_f32 v[114:115], v[114:115], v[74:75], v[90:91]
	v_cvt_pk_bf16_f32 v112, v112, v113
	v_cvt_pk_bf16_f32 v113, v114, v115
	global_store_dwordx2 v[140:141], v[112:113], off offset:1536 nt
	global_load_dwordx4 v[112:115], v[136:137], off offset:3072 nt
	s_waitcnt vmcnt(18)
	v_sub_f32_e32 v117, v117, v16
	v_sub_f32_e32 v116, v116, v16
	v_sub_f32_e32 v119, v119, v16
	v_sub_f32_e32 v118, v118, v16
	v_pk_mul_f32 v[116:117], v[116:117], v[18:19] op_sel_hi:[1,0]
	v_pk_mul_f32 v[118:119], v[118:119], v[18:19] op_sel_hi:[1,0]
	v_pk_fma_f32 v[116:117], v[116:117], v[60:61], v[76:77]
	v_pk_fma_f32 v[118:119], v[118:119], v[62:63], v[78:79]
	v_cvt_pk_bf16_f32 v116, v116, v117
	v_cvt_pk_bf16_f32 v117, v118, v119
	global_store_dwordx2 v[142:143], v[116:117], off nt
	global_load_dwordx4 v[116:119], v[138:139], off nt
	s_waitcnt vmcnt(18)
	v_sub_f32_e32 v121, v121, v16
	v_sub_f32_e32 v120, v120, v16
	v_sub_f32_e32 v123, v123, v16
	v_sub_f32_e32 v122, v122, v16
	v_pk_mul_f32 v[120:121], v[120:121], v[18:19] op_sel_hi:[1,0]
	v_pk_mul_f32 v[122:123], v[122:123], v[18:19] op_sel_hi:[1,0]
	v_pk_fma_f32 v[120:121], v[120:121], v[64:65], v[80:81]
	v_pk_fma_f32 v[122:123], v[122:123], v[66:67], v[82:83]
	v_cvt_pk_bf16_f32 v120, v120, v121
	v_cvt_pk_bf16_f32 v121, v122, v123
	global_store_dwordx2 v[142:143], v[120:121], off offset:512 nt
	global_load_dwordx4 v[120:123], v[138:139], off offset:1024 nt
	s_waitcnt vmcnt(18)
	v_sub_f32_e32 v125, v125, v16
	v_sub_f32_e32 v124, v124, v16
	v_sub_f32_e32 v127, v127, v16
	v_sub_f32_e32 v126, v126, v16
	v_pk_mul_f32 v[124:125], v[124:125], v[18:19] op_sel_hi:[1,0]
	v_pk_mul_f32 v[126:127], v[126:127], v[18:19] op_sel_hi:[1,0]
	v_pk_fma_f32 v[124:125], v[124:125], v[68:69], v[84:85]
	v_pk_fma_f32 v[126:127], v[126:127], v[70:71], v[86:87]
	v_cvt_pk_bf16_f32 v124, v124, v125
	v_cvt_pk_bf16_f32 v125, v126, v127
	global_store_dwordx2 v[142:143], v[124:125], off offset:1024 nt
	global_load_dwordx4 v[124:127], v[138:139], off offset:2048 nt
	s_waitcnt vmcnt(18)
	v_sub_f32_e32 v129, v129, v16
	v_sub_f32_e32 v128, v128, v16
	v_sub_f32_e32 v131, v131, v16
	v_sub_f32_e32 v130, v130, v16
	v_pk_mul_f32 v[128:129], v[128:129], v[18:19] op_sel_hi:[1,0]
	v_pk_mul_f32 v[130:131], v[130:131], v[18:19] op_sel_hi:[1,0]
	v_pk_fma_f32 v[128:129], v[128:129], v[72:73], v[88:89]
	v_pk_fma_f32 v[130:131], v[130:131], v[74:75], v[90:91]
	v_cvt_pk_bf16_f32 v128, v128, v129
	v_cvt_pk_bf16_f32 v129, v130, v131
	global_store_dwordx2 v[142:143], v[128:129], off offset:1536 nt
	global_load_dwordx4 v[128:131], v[138:139], off offset:3072 nt
	s_and_b64 vcc, exec, s[26:27]
	s_cbranch_vccnz .Lln1_loop
	s_waitcnt vmcnt(0)

.LBB0_1874:
	s_or_b64 exec, exec, s[0:1]
	s_barrier
	v_readlane_b32 s1, v251, 2
	v_readfirstlane_b32 s0, v228
	s_ashr_i32 s0, s0, 6
	s_add_i32 s10, s0, s1
	s_cmp_gt_i32 s10, 0x100ff
	s_cbranch_scc1 .LBB0_1883
	v_and_b32_e32 v1, 63, v228
	v_mov_b32_e32 v0, 0
	v_lshlrev_b32_e32 v4, 3, v1
	v_mov_b32_e32 v5, v0
	v_lshlrev_b32_e32 v10, 4, v1
	v_mov_b32_e32 v11, v0
	v_cmp_gt_u32_e64 s[0:1], 16, v1
	v_lshl_add_u64 v[2:3], s[96:97], 0, v[4:5]
	v_lshl_add_u64 v[4:5], s[16:17], 0, v[4:5]
	v_lshl_add_u64 v[6:7], s[84:85], 0, v[10:11]
	v_lshl_add_u64 v[8:9], s[86:87], 0, v[10:11]
	v_lshl_add_u64 v[10:11], s[88:89], 0, v[10:11]
	s_mov_b32 s4, 0x3a800000
	s_mov_b32 s5, 0xf800000
	v_mov_b32_e32 v30, 0x260
	global_load_dwordx4 v[60:63], v[6:7], off
	global_load_dwordx4 v[76:79], v[8:9], off
	global_load_dwordx4 v[64:67], v[6:7], off offset:1024
	global_load_dwordx4 v[80:83], v[8:9], off offset:1024
	global_load_dwordx4 v[68:71], v[6:7], off offset:2048
	global_load_dwordx4 v[84:87], v[8:9], off offset:2048
	global_load_dwordx4 v[72:75], v[6:7], off offset:3072
	global_load_dwordx4 v[88:91], v[8:9], off offset:3072
	v_mov_b32_e32 v170, 0
	v_mov_b32_e32 v171, 0
	v_mov_b32_e32 v172, 0
	v_mov_b32_e32 v173, 0
	s_add_i32 s14, s10, s76
	s_cmp_lt_i32 s14, 0x10100
	s_cselect_b32 s14, s14, s10
	s_ashr_i32 s11, s10, 31
	s_ashr_i32 s15, s14, 31
	s_lshl_b64 s[8:9], s[10:11], 11
	v_lshl_add_u64 v[174:175], v[2:3], 0, s[8:9]
	s_lshl_b64 s[8:9], s[14:15], 11
	v_lshl_add_u64 v[176:177], v[2:3], 0, s[8:9]
	s_lshl_b64 s[8:9], s[10:11], 7
	v_lshl_add_u64 v[178:179], v[4:5], 0, s[8:9]
	s_lshl_b64 s[8:9], s[14:15], 7
	v_lshl_add_u64 v[180:181], v[4:5], 0, s[8:9]
	s_and_saveexec_b64 s[8:9], s[0:1]
	global_load_dwordx2 v[170:171], v[178:179], off
	global_load_dwordx2 v[172:173], v[180:181], off
	s_mov_b64 exec, s[8:9]
	global_load_dwordx2 v[100:101], v[174:175], off nt
	global_load_dwordx2 v[102:103], v[174:175], off offset:512 nt
	global_load_dwordx2 v[104:105], v[174:175], off offset:1024 nt
	global_load_dwordx2 v[106:107], v[174:175], off offset:1536 nt
	global_load_dwordx2 v[108:109], v[176:177], off nt
	global_load_dwordx2 v[110:111], v[176:177], off offset:512 nt
	global_load_dwordx2 v[112:113], v[176:177], off offset:1024 nt
	global_load_dwordx2 v[114:115], v[176:177], off offset:1536 nt
	s_waitcnt vmcnt(0)
.Lln2_loop:
	s_waitcnt vmcnt(16)
	v_mov_b32_e32 v14, v170
	v_mov_b32_e32 v12, v171
	v_mov_b32_e32 v154, v172
	v_mov_b32_e32 v152, v173
	v_mov_b32_e32 v13, v14
	s_nop 0
	s_nop 0
	v_mov_b32_dpp v13, v13 quad_perm:[1,0,3,2] row_mask:0xf bank_mask:0xf
	v_add_f32_e32 v13, v14, v13
	v_mov_b32_e32 v14, v13
	s_nop 1
	v_mov_b32_dpp v14, v14 quad_perm:[2,3,0,1] row_mask:0xf bank_mask:0xf
	v_add_f32_e32 v13, v13, v14
	v_mov_b32_e32 v14, v13
	s_nop 1
	v_mov_b32_dpp v14, v14 row_ror:4 row_mask:0xf bank_mask:0xf
	v_add_f32_e32 v13, v13, v14
	v_mov_b32_e32 v14, v13
	s_nop 1
	v_mov_b32_dpp v14, v14 row_ror:8 row_mask:0xf bank_mask:0xf
	v_add_f32_e32 v13, v13, v14
	s_nop 0
	v_readfirstlane_b32 s7, v13
	v_mov_b32_e32 v13, v12
	s_nop 1
	v_mov_b32_dpp v13, v13 quad_perm:[1,0,3,2] row_mask:0xf bank_mask:0xf
	v_add_f32_e32 v12, v12, v13
	v_mov_b32_e32 v13, v12
	s_nop 1
	v_mov_b32_dpp v13, v13 quad_perm:[2,3,0,1] row_mask:0xf bank_mask:0xf
	v_add_f32_e32 v12, v12, v13
	v_mov_b32_e32 v13, v12
	s_nop 1
	v_mov_b32_dpp v13, v13 row_ror:4 row_mask:0xf bank_mask:0xf
	v_add_f32_e32 v12, v12, v13
	v_mov_b32_e32 v13, v12
	s_nop 1
	v_mov_b32_dpp v13, v13 row_ror:8 row_mask:0xf bank_mask:0xf
	v_add_f32_e32 v12, v12, v13
	s_nop 0
	v_readfirstlane_b32 s12, v12
	v_cvt_i32_f32_e32 v12, s7
	v_cvt_f32_i32_e32 v13, v12
	v_cvt_i32_f32_e32 v14, s12
	v_cvt_f32_i32_e32 v12, v14
	v_pk_mul_f32 v[40:41], v[12:13], s[4:5] op_sel_hi:[1,0]
	s_nop 0
	v_fma_f32 v12, -v41, v41, v40
	v_max_f32_e32 v12, 0, v12
	v_add_f32_e32 v12, 0x3727c5ac, v12
	v_mul_f32_e32 v13, 0x4f800000, v12
	v_cmp_gt_f32_e32 vcc, s5, v12
	s_nop 1
	v_cndmask_b32_e32 v12, v12, v13, vcc
	v_sqrt_f32_e32 v13, v12
	s_nop 0
	v_add_u32_e32 v14, -1, v13
	v_fma_f32 v16, -v14, v13, v12
	v_cmp_ge_f32_e64 s[2:3], 0, v16
	v_add_u32_e32 v16, 1, v13
	s_nop 0
	v_cndmask_b32_e64 v14, v13, v14, s[2:3]
	v_fma_f32 v13, -v16, v13, v12
	v_cmp_lt_f32_e64 s[2:3], 0, v13
	s_nop 1
	v_cndmask_b32_e64 v13, v14, v16, s[2:3]
	v_mul_f32_e32 v14, 0x37800000, v13
	v_cndmask_b32_e32 v13, v13, v14, vcc
	v_cmp_class_f32_e32 vcc, v12, v30
	s_nop 1
	v_cndmask_b32_e32 v14, v13, v12, vcc
	v_div_scale_f32 v31, s[2:3], v14, v14, 1.0
	v_rcp_f32_e32 v40, v31
	s_nop 0
	s_nop 0
	s_nop 0
	s_nop 0
	s_nop 0
	v_fma_f32 v42, -v31, v40, 1.0
	v_fmac_f32_e32 v40, v42, v40
	v_div_scale_f32 v42, vcc, 1.0, v14, 1.0
	v_mul_f32_e32 v43, v42, v40
	v_fma_f32 v44, -v31, v43, v42
	v_fmac_f32_e32 v43, v44, v40
	v_fma_f32 v31, -v31, v43, v42
	v_div_fmas_f32 v31, v31, v40, v43
	v_div_fixup_f32 v14, v31, v14, 1.0
	v_mov_b32_e32 v153, v154
	s_nop 0
	s_nop 0
	v_mov_b32_dpp v153, v153 quad_perm:[1,0,3,2] row_mask:0xf bank_mask:0xf
	v_add_f32_e32 v153, v154, v153
	v_mov_b32_e32 v154, v153
	s_nop 1
	v_mov_b32_dpp v154, v154 quad_perm:[2,3,0,1] row_mask:0xf bank_mask:0xf
	v_add_f32_e32 v153, v153, v154
	v_mov_b32_e32 v154, v153
	s_nop 1
	v_mov_b32_dpp v154, v154 row_ror:4 row_mask:0xf bank_mask:0xf
	v_add_f32_e32 v153, v153, v154
	v_mov_b32_e32 v154, v153
	s_nop 1
	v_mov_b32_dpp v154, v154 row_ror:8 row_mask:0xf bank_mask:0xf
	v_add_f32_e32 v153, v153, v154
	s_nop 0
	v_readfirstlane_b32 s7, v153
	v_mov_b32_e32 v153, v152
	s_nop 1
	v_mov_b32_dpp v153, v153 quad_perm:[1,0,3,2] row_mask:0xf bank_mask:0xf
	v_add_f32_e32 v152, v152, v153
	v_mov_b32_e32 v153, v152
	s_nop 1
	v_mov_b32_dpp v153, v153 quad_perm:[2,3,0,1] row_mask:0xf bank_mask:0xf
	v_add_f32_e32 v152, v152, v153
	v_mov_b32_e32 v153, v152
	s_nop 1
	v_mov_b32_dpp v153, v153 row_ror:4 row_mask:0xf bank_mask:0xf
	v_add_f32_e32 v152, v152, v153
	v_mov_b32_e32 v153, v152
	s_nop 1
	v_mov_b32_dpp v153, v153 row_ror:8 row_mask:0xf bank_mask:0xf
	v_add_f32_e32 v152, v152, v153
	s_nop 0
	v_readfirstlane_b32 s12, v152
	v_cvt_i32_f32_e32 v152, s7
	v_cvt_f32_i32_e32 v153, v152
	v_cvt_i32_f32_e32 v154, s12
	v_cvt_f32_i32_e32 v152, v154
	v_pk_mul_f32 v[160:161], v[152:153], s[4:5] op_sel_hi:[1,0]
	s_nop 0
	v_fma_f32 v152, -v161, v161, v160
	v_max_f32_e32 v152, 0, v152
	v_add_f32_e32 v152, 0x3727c5ac, v152
	v_mul_f32_e32 v153, 0x4f800000, v152
	v_cmp_gt_f32_e32 vcc, s5, v152
	s_nop 1
	v_cndmask_b32_e32 v152, v152, v153, vcc
	v_sqrt_f32_e32 v153, v152
	s_nop 0
	v_add_u32_e32 v154, -1, v153
	v_fma_f32 v156, -v154, v153, v152
	v_cmp_ge_f32_e64 s[2:3], 0, v156
	v_add_u32_e32 v156, 1, v153
	s_nop 0
	v_cndmask_b32_e64 v154, v153, v154, s[2:3]
	v_fma_f32 v153, -v156, v153, v152
	v_cmp_lt_f32_e64 s[2:3], 0, v153
	s_nop 1
	v_cndmask_b32_e64 v153, v154, v156, s[2:3]
	v_mul_f32_e32 v154, 0x37800000, v153
	v_cndmask_b32_e32 v153, v153, v154, vcc
	v_cmp_class_f32_e32 vcc, v152, v30
	s_nop 1
	v_cndmask_b32_e32 v154, v153, v152, vcc
	v_div_scale_f32 v157, s[2:3], v154, v154, 1.0
	v_rcp_f32_e32 v160, v157
	s_nop 0
	s_nop 0
	s_nop 0
	s_nop 0
	s_nop 0
	v_fma_f32 v162, -v157, v160, 1.0
	v_fmac_f32_e32 v160, v162, v160
	v_div_scale_f32 v162, vcc, 1.0, v154, 1.0
	v_mul_f32_e32 v163, v162, v160
	v_fma_f32 v164, -v157, v163, v162
	v_fmac_f32_e32 v163, v164, v160
	v_fma_f32 v157, -v157, v163, v162
	v_div_fmas_f32 v157, v157, v160, v163
	v_div_fixup_f32 v154, v157, v154, 1.0
	s_lshl_b64 s[8:9], s[10:11], 12
	v_lshl_add_u64 v[182:183], v[10:11], 0, s[8:9]
	s_lshl_b64 s[8:9], s[14:15], 12
	v_lshl_add_u64 v[184:185], v[10:11], 0, s[8:9]
	s_lshl_b32 s8, s76, 1
	s_add_i32 s10, s10, s8
	s_add_i32 s14, s10, s76
	s_cmp_lt_i32 s14, 0x10100
	s_cselect_b32 s14, s14, s10
	s_cmp_lt_i32 s10, 0x10100
	s_cselect_b64 s[20:21], -1, 0
	s_cbranch_scc0 .Lln2_dummy
	s_ashr_i32 s11, s10, 31
	s_ashr_i32 s15, s14, 31
	s_lshl_b64 s[8:9], s[10:11], 11
	v_lshl_add_u64 v[174:175], v[2:3], 0, s[8:9]
	s_lshl_b64 s[8:9], s[14:15], 11
	v_lshl_add_u64 v[176:177], v[2:3], 0, s[8:9]
	s_lshl_b64 s[8:9], s[10:11], 7
	v_lshl_add_u64 v[178:179], v[4:5], 0, s[8:9]
	s_lshl_b64 s[8:9], s[14:15], 7
	v_lshl_add_u64 v[180:181], v[4:5], 0, s[8:9]
	s_branch .Lln2_addr
.Lln2_dummy:
	v_mov_b64_e32 v[174:175], v[6:7]
	v_mov_b64_e32 v[176:177], v[6:7]
	v_mov_b64_e32 v[178:179], v[4:5]
	v_mov_b64_e32 v[180:181], v[4:5]
.Lln2_addr:
	s_and_saveexec_b64 s[8:9], s[0:1]
	global_load_dwordx2 v[170:171], v[178:179], off
	global_load_dwordx2 v[172:173], v[180:181], off
	s_mov_b64 exec, s[8:9]
	s_waitcnt vmcnt(16)
	v_lshlrev_b32_e32 v186, 16, v100
	v_and_b32_e32 v187, 0xffff0000, v100
	v_lshlrev_b32_e32 v188, 16, v101
	v_and_b32_e32 v189, 0xffff0000, v101
	v_sub_f32_e32 v186, v186, v41
	v_sub_f32_e32 v187, v187, v41
	v_sub_f32_e32 v188, v188, v41
	v_sub_f32_e32 v189, v189, v41
	v_pk_mul_f32 v[186:187], v[186:187], v[14:15] op_sel_hi:[1,0]
	v_pk_mul_f32 v[188:189], v[188:189], v[14:15] op_sel_hi:[1,0]
	v_pk_fma_f32 v[120:121], v[60:61], v[186:187], v[76:77]
	v_pk_fma_f32 v[122:123], v[62:63], v[188:189], v[78:79]
	global_store_dwordx4 v[182:183], v[120:123], off nt
	global_load_dwordx2 v[100:101], v[174:175], off nt
	s_waitcnt vmcnt(16)
	v_lshlrev_b32_e32 v186, 16, v102
	v_and_b32_e32 v187, 0xffff0000, v102
	v_lshlrev_b32_e32 v188, 16, v103
	v_and_b32_e32 v189, 0xffff0000, v103
	v_sub_f32_e32 v186, v186, v41
	v_sub_f32_e32 v187, v187, v41
	v_sub_f32_e32 v188, v188, v41
	v_sub_f32_e32 v189, v189, v41
	v_pk_mul_f32 v[186:187], v[186:187], v[14:15] op_sel_hi:[1,0]
	v_pk_mul_f32 v[188:189], v[188:189], v[14:15] op_sel_hi:[1,0]
	v_pk_fma_f32 v[124:125], v[64:65], v[186:187], v[80:81]
	v_pk_fma_f32 v[126:127], v[66:67], v[188:189], v[82:83]
	global_store_dwordx4 v[182:183], v[124:127], off offset:1024 nt
	global_load_dwordx2 v[102:103], v[174:175], off offset:512 nt
	s_waitcnt vmcnt(16)
	v_lshlrev_b32_e32 v186, 16, v104
	v_and_b32_e32 v187, 0xffff0000, v104
	v_lshlrev_b32_e32 v188, 16, v105
	v_and_b32_e32 v189, 0xffff0000, v105
	v_sub_f32_e32 v186, v186, v41
	v_sub_f32_e32 v187, v187, v41
	v_sub_f32_e32 v188, v188, v41
	v_sub_f32_e32 v189, v189, v41
	v_pk_mul_f32 v[186:187], v[186:187], v[14:15] op_sel_hi:[1,0]
	v_pk_mul_f32 v[188:189], v[188:189], v[14:15] op_sel_hi:[1,0]
	v_pk_fma_f32 v[128:129], v[68:69], v[186:187], v[84:85]
	v_pk_fma_f32 v[130:131], v[70:71], v[188:189], v[86:87]
	global_store_dwordx4 v[182:183], v[128:131], off offset:2048 nt
	global_load_dwordx2 v[104:105], v[174:175], off offset:1024 nt
	s_waitcnt vmcnt(16)
	v_lshlrev_b32_e32 v186, 16, v106
	v_and_b32_e32 v187, 0xffff0000, v106
	v_lshlrev_b32_e32 v188, 16, v107
	v_and_b32_e32 v189, 0xffff0000, v107
	v_sub_f32_e32 v186, v186, v41
	v_sub_f32_e32 v187, v187, v41
	v_sub_f32_e32 v188, v188, v41
	v_sub_f32_e32 v189, v189, v41
	v_pk_mul_f32 v[186:187], v[186:187], v[14:15] op_sel_hi:[1,0]
	v_pk_mul_f32 v[188:189], v[188:189], v[14:15] op_sel_hi:[1,0]
	v_pk_fma_f32 v[132:133], v[72:73], v[186:187], v[88:89]
	v_pk_fma_f32 v[134:135], v[74:75], v[188:189], v[90:91]
	global_store_dwordx4 v[182:183], v[132:135], off offset:3072 nt
	global_load_dwordx2 v[106:107], v[174:175], off offset:1536 nt
	s_waitcnt vmcnt(16)
	v_lshlrev_b32_e32 v186, 16, v108
	v_and_b32_e32 v187, 0xffff0000, v108
	v_lshlrev_b32_e32 v188, 16, v109
	v_and_b32_e32 v189, 0xffff0000, v109
	v_sub_f32_e32 v186, v186, v161
	v_sub_f32_e32 v187, v187, v161
	v_sub_f32_e32 v188, v188, v161
	v_sub_f32_e32 v189, v189, v161
	v_pk_mul_f32 v[186:187], v[186:187], v[154:155] op_sel_hi:[1,0]
	v_pk_mul_f32 v[188:189], v[188:189], v[154:155] op_sel_hi:[1,0]
	v_pk_fma_f32 v[136:137], v[60:61], v[186:187], v[76:77]
	v_pk_fma_f32 v[138:139], v[62:63], v[188:189], v[78:79]
	global_store_dwordx4 v[184:185], v[136:139], off nt
	global_load_dwordx2 v[108:109], v[176:177], off nt
	s_waitcnt vmcnt(16)
	v_lshlrev_b32_e32 v186, 16, v110
	v_and_b32_e32 v187, 0xffff0000, v110
	v_lshlrev_b32_e32 v188, 16, v111
	v_and_b32_e32 v189, 0xffff0000, v111
	v_sub_f32_e32 v186, v186, v161
	v_sub_f32_e32 v187, v187, v161
	v_sub_f32_e32 v188, v188, v161
	v_sub_f32_e32 v189, v189, v161
	v_pk_mul_f32 v[186:187], v[186:187], v[154:155] op_sel_hi:[1,0]
	v_pk_mul_f32 v[188:189], v[188:189], v[154:155] op_sel_hi:[1,0]
	v_pk_fma_f32 v[140:141], v[64:65], v[186:187], v[80:81]
	v_pk_fma_f32 v[142:143], v[66:67], v[188:189], v[82:83]
	global_store_dwordx4 v[184:185], v[140:143], off offset:1024 nt
	global_load_dwordx2 v[110:111], v[176:177], off offset:512 nt
	s_waitcnt vmcnt(16)
	v_lshlrev_b32_e32 v186, 16, v112
	v_and_b32_e32 v187, 0xffff0000, v112
	v_lshlrev_b32_e32 v188, 16, v113
	v_and_b32_e32 v189, 0xffff0000, v113
	v_sub_f32_e32 v186, v186, v161
	v_sub_f32_e32 v187, v187, v161
	v_sub_f32_e32 v188, v188, v161
	v_sub_f32_e32 v189, v189, v161
	v_pk_mul_f32 v[186:187], v[186:187], v[154:155] op_sel_hi:[1,0]
	v_pk_mul_f32 v[188:189], v[188:189], v[154:155] op_sel_hi:[1,0]
	v_pk_fma_f32 v[144:145], v[68:69], v[186:187], v[84:85]
	v_pk_fma_f32 v[146:147], v[70:71], v[188:189], v[86:87]
	global_store_dwordx4 v[184:185], v[144:147], off offset:2048 nt
	global_load_dwordx2 v[112:113], v[176:177], off offset:1024 nt
	s_waitcnt vmcnt(16)
	v_lshlrev_b32_e32 v186, 16, v114
	v_and_b32_e32 v187, 0xffff0000, v114
	v_lshlrev_b32_e32 v188, 16, v115
	v_and_b32_e32 v189, 0xffff0000, v115
	v_sub_f32_e32 v186, v186, v161
	v_sub_f32_e32 v187, v187, v161
	v_sub_f32_e32 v188, v188, v161
	v_sub_f32_e32 v189, v189, v161
	v_pk_mul_f32 v[186:187], v[186:187], v[154:155] op_sel_hi:[1,0]
	v_pk_mul_f32 v[188:189], v[188:189], v[154:155] op_sel_hi:[1,0]
	v_pk_fma_f32 v[148:149], v[72:73], v[186:187], v[88:89]
	v_pk_fma_f32 v[150:151], v[74:75], v[188:189], v[90:91]
	global_store_dwordx4 v[184:185], v[148:151], off offset:3072 nt
	global_load_dwordx2 v[114:115], v[176:177], off offset:1536 nt
	s_and_b64 vcc, exec, s[20:21]
	s_cbranch_vccnz .Lln2_loop
	s_waitcnt vmcnt(0)
